# half-tile tail loops also reload each staging register right after its LDS write; prep weight-transpose loop software-pipelined (all tile loads in flight, next tile loads before current tile stores)
# speedup vs baseline: 1.0708x; 1.0034x over previous
; DI void phase_prep(const Params& p, u16* sm, int wv) {
;     ...
;   for (int t = bid; t < T_IN + T_OUT; t += nb) {
;     const float* src; u16* dst; int N, kt, nt; const float* gsc = nullptr;
;     if (t < T_IN) {
;       int l = t / 832, rr = t % 832; kt = rr / 52; nt = rr % 52; N = DIN;
;       src = p.w_in + (size_t)l * 1024 * DIN; dst = p.wtin + (size_t)l * DIN * 1024; gsc = p.norm_g + l * DM;
;     } else {
;       int u = t - T_IN; int l = u / 256, rr = u % 256; kt = rr / 16; nt = rr % 16; N = 1024;
;       src = p.w_out + (size_t)l * 1024 * 1024; dst = p.wtout + (size_t)l * 1024 * 1024;
;     }
.LBB0_20:
	s_mov_b32 s26, 0
.Lprep_top:
	s_cmpk_gt_i32 s19, 0x87f
	s_cbranch_scc1 .Lprep_store
	s_cmpk_gt_i32 s19, 0x67f
	s_mov_b64 s[8:9], -1
	s_cbranch_scc0 .LBB0_22
	s_add_i32 s0, s19, 0xfffff980
	s_lshr_b32 s4, s0, 8
	s_bfe_u32 s10, s0, 0x40004
	s_and_b32 s11, s19, 15
	s_lshl_b64 s[0:1], s[4:5], 22
	s_add_u32 s0, s50, s0
	s_addc_u32 s1, s51, s1
	s_lshl_b64 s[6:7], s[4:5], 21
	s_add_u32 s6, s58, s6
	s_addc_u32 s7, s59, s7
	s_mov_b64 s[8:9], 0

; DI void phase_prep(const Params& p, u16* sm, int wv) {
;     ...
;     __syncthreads();
; #pragma unroll
;     for (int i = 0; i < 4; ++i) {
;       const int k = i * 16 + (tid >> 4), n4 = (tid & 15) * 4;
;       const f32x4 v = __builtin_nontemporal_load((const f32x4*)(src + (size_t)(kt * 64 + k) * N + nt * 64 + n4));
;       const float gk = gsc ? gsc[kt * 64 + k] : 1.f;
;       smf[(n4 + 0) * 65 + k] = v[0] * gk; smf[(n4 + 1) * 65 + k] = v[1] * gk;
;       smf[(n4 + 2) * 65 + k] = v[2] * gk; smf[(n4 + 3) * 65 + k] = v[3] * gk;
;     }
;     __syncthreads();
; #pragma unroll
;     for (int j = 0; j < 2; ++j) {
;       const int c = tid + 256 * j, kc = c & 7, n = c >> 3;
;       const float* q = smf + n * 65 + kc * 8;
;       u32x4 o = {pk2(q[0], q[1]), pk2(q[2], q[3]), pk2(q[4], q[5]), pk2(q[6], q[7])};
;       *(u32x4*)(dst + (size_t)(nt * 64 + n) * 1024 + kt * 64 + kc * 8) = o;
;     }
.LBB0_25:
	s_lshl_b32 s8, s11, 6
	s_ashr_i32 s9, s8, 31
	s_lshl_b32 s10, s10, 6
	s_lshl_b64 s[16:17], s[8:9], 2
	s_add_u32 s0, s0, s16
	s_addc_u32 s1, s1, s17
	v_add_u32_e32 v16, s10, v19
	v_lshl_add_u64 v[12:13], s[0:1], 0, v[8:9]
	v_mad_i64_i32 v[0:1], s[0:1], s12, v16, 0
	v_lshl_add_u64 v[0:1], v[0:1], 2, v[12:13]
	global_load_dwordx4 v[160:163], v[0:1], off nt
	v_add_u32_e32 v0, 16, v16
	v_mad_i64_i32 v[0:1], s[0:1], s12, v0, 0
	v_lshl_add_u64 v[0:1], v[0:1], 2, v[12:13]
	global_load_dwordx4 v[164:167], v[0:1], off nt
	v_add_u32_e32 v0, 32, v16
	v_mad_i64_i32 v[0:1], s[0:1], s12, v0, 0
	v_lshl_add_u64 v[0:1], v[0:1], 2, v[12:13]
	global_load_dwordx4 v[168:171], v[0:1], off nt
	v_add_u32_e32 v0, 48, v16
	v_mad_i64_i32 v[0:1], s[0:1], s12, v0, 0
	v_lshl_add_u64 v[0:1], v[0:1], 2, v[12:13]
	global_load_dwordx4 v[172:175], v[0:1], off nt
	s_mov_b32 s20, s6
	s_mov_b32 s21, s7
	s_mov_b32 s22, s10
	s_mov_b32 s23, s8
	s_cmp_eq_u64 s[14:15], 0
	s_cbranch_scc1 .Lprep_nog
	v_ashrrev_i32_e32 v17, 31, v16
	v_lshl_add_u64 v[14:15], v[16:17], 2, s[14:15]
	global_load_dword v176, v[14:15], off
	global_load_dword v177, v[14:15], off offset:64
	global_load_dword v178, v[14:15], off offset:128
	global_load_dword v179, v[14:15], off offset:192
	s_branch .Lprep_store
.Lprep_nog:
	v_mov_b32_e32 v176, 1.0
	v_mov_b32_e32 v177, 1.0
	v_mov_b32_e32 v178, 1.0
	v_mov_b32_e32 v179, 1.0
.Lprep_store:
	s_cmp_eq_u32 s26, 0
	s_cbranch_scc1 .Lprep_write
	ds_read2_b32 v[0:1], v23 offset1:1
	ds_read2_b32 v[2:3], v23 offset0:2 offset1:3
	ds_read2_b32 v[4:5], v23 offset0:4 offset1:5
	ds_read2_b32 v[6:7], v23 offset0:6 offset1:7
	s_ashr_i32 s31, s30, 31
	s_lshl_b64 s[30:31], s[30:31], 1
	s_add_u32 s30, s24, s30
	s_addc_u32 s31, s25, s31
	s_waitcnt lgkmcnt(3)
	v_cvt_pk_bf16_f32 v0, v0, v1
	s_waitcnt lgkmcnt(2)
	v_cvt_pk_bf16_f32 v1, v2, v3
	s_waitcnt lgkmcnt(1)
	v_cvt_pk_bf16_f32 v2, v4, v5
	v_add_u32_e32 v4, s28, v20
	v_ashrrev_i32_e32 v5, 31, v4
	v_lshl_add_u64 v[12:13], s[30:31], 0, v[10:11]
	s_waitcnt lgkmcnt(0)
	v_cvt_pk_bf16_f32 v3, v6, v7
	v_lshlrev_b64 v[4:5], 11, v[4:5]
	ds_read2_b32 v[6:7], v24 offset1:1
	ds_read2_b32 v[14:15], v24 offset0:2 offset1:3
	ds_read2_b32 v[16:17], v24 offset0:4 offset1:5
	ds_read2_b32 v[26:27], v24 offset0:6 offset1:7
	v_lshl_add_u64 v[4:5], v[12:13], 0, v[4:5]
	global_store_dwordx4 v[4:5], v[0:3], off
	v_add_u32_e32 v4, s28, v22
	v_ashrrev_i32_e32 v5, 31, v4
	v_lshlrev_b64 v[4:5], 11, v[4:5]
	s_waitcnt lgkmcnt(3)
	v_cvt_pk_bf16_f32 v0, v6, v7
	s_waitcnt lgkmcnt(2)
	v_cvt_pk_bf16_f32 v1, v14, v15
	s_waitcnt lgkmcnt(1)
	v_cvt_pk_bf16_f32 v2, v16, v17
	s_waitcnt lgkmcnt(0)
	v_cvt_pk_bf16_f32 v3, v26, v27
	v_lshl_add_u64 v[4:5], v[12:13], 0, v[4:5]
	s_cmpk_gt_i32 s19, 0x87f
	global_store_dwordx4 v[4:5], v[0:3], off
	s_cbranch_scc1 .LBB0_33
.Lprep_write:
	s_waitcnt vmcnt(0)
	s_barrier
	v_mul_f32_e32 v0, v160, v176
	v_mul_f32_e32 v1, v161, v176
	ds_write2_b32 v21, v0, v1 offset1:65
	v_mul_f32_e32 v0, v162, v176
	v_mul_f32_e32 v1, v163, v176
	ds_write2_b32 v21, v0, v1 offset0:130 offset1:195
	v_mul_f32_e32 v0, v164, v177
	v_mul_f32_e32 v1, v165, v177
	ds_write2_b32 v21, v0, v1 offset0:16 offset1:81
	v_mul_f32_e32 v0, v166, v177
	v_mul_f32_e32 v1, v167, v177
	ds_write2_b32 v21, v0, v1 offset0:146 offset1:211
	v_mul_f32_e32 v0, v168, v178
	v_mul_f32_e32 v1, v169, v178
	ds_write2_b32 v21, v0, v1 offset0:32 offset1:97
	v_mul_f32_e32 v0, v170, v178
	v_mul_f32_e32 v1, v171, v178
	ds_write2_b32 v21, v0, v1 offset0:162 offset1:227
	v_mul_f32_e32 v0, v172, v179
	v_mul_f32_e32 v1, v173, v179
	ds_write2_b32 v21, v0, v1 offset0:48 offset1:113
	v_mul_f32_e32 v0, v174, v179
	v_mul_f32_e32 v1, v175, v179
	ds_write2_b32 v21, v0, v1 offset0:178 offset1:243
	s_waitcnt lgkmcnt(0)
	s_barrier
	s_mov_b32 s24, s20
	s_mov_b32 s25, s21
	s_mov_b32 s30, s22
	s_mov_b32 s28, s23
	s_mov_b32 s26, 1
	s_add_i32 s19, s19, s86
	s_branch .Lprep_top

; template <bool VT>
; DI void gemm_mainloop(f32x4 (&acc)[8][4], const char* abase, const char* bbase, unsigned toff, u16* sA, u16* sB, int loff, int wm, int wn, int fr, int fq) {
;     ...
;   for (int kt = 0; kt < 16; ++kt) {
;     __syncthreads();
; #pragma unroll
;     for (int i = 0; i < 8; ++i) *(u32x4*)(sA + loff + i * 32 * GSTR) = ra[i];
; #pragma unroll
;     for (int i = 0; i < 4; ++i) *(u32x4*)(sB + loff + i * 32 * GSTR) = rb[i];
;     __syncthreads();
;     if (kt + 1 < 16) {
;       const int ko = (kt + 1) * 128;
; #pragma unroll
;       for (int i = 0; i < 8; ++i) ra[i] = __builtin_amdgcn_raw_buffer_load_b128(ra_rs, (int)toff, i * 65536 + ko, 0);
; #pragma unroll
;       for (int i = 0; i < 4; ++i) rb[i] = __builtin_amdgcn_raw_buffer_load_b128(rb_rs, (int)toff, i * 65536 + ko, 0);
;     }
;     __builtin_amdgcn_s_setprio(1);
;     gemm_kslab<VT>(acc, sA, sB, wm, wn, fr, fq);
;     __builtin_amdgcn_s_setprio(0);
.Lh0_loop:
	s_barrier
	s_addk_i32 s42, 0x100
	s_addk_i32 s43, 0x100
	s_addk_i32 s46, 0x100
	s_addk_i32 s47, 0x100
	s_addk_i32 s70, 0x100
	s_addk_i32 s71, 0x100
	s_waitcnt vmcnt(15)
	ds_write_b128 v180, v[146:149] offset:20480
	buffer_load_dwordx4 v[146:149], v0, s[64:67], s42 offen
	s_waitcnt vmcnt(15)
	ds_write_b128 v180, v[150:153] offset:25600
	buffer_load_dwordx4 v[150:153], v0, s[64:67], s43 offen
	s_waitcnt vmcnt(15)
	ds_write_b128 v180, v[130:133]
	buffer_load_dwordx4 v[130:133], v0, s[64:67], s46 offen
	s_waitcnt vmcnt(15)
	ds_write_b128 v180, v[138:141] offset:5120
	buffer_load_dwordx4 v[138:141], v0, s[64:67], s47 offen
	s_waitcnt vmcnt(15)
	ds_write_b128 v180, v[162:165] offset:40960
	buffer_load_dwordx4 v[162:165], v0, s[84:87], s46 offen
	s_waitcnt vmcnt(15)
	ds_write_b128 v180, v[170:173] offset:46080
	buffer_load_dwordx4 v[170:173], v0, s[84:87], s47 offen
	s_waitcnt vmcnt(15)
	ds_write_b128 v180, v[166:169] offset:51200
	buffer_load_dwordx4 v[166:169], v0, s[84:87], s70 offen
	s_waitcnt vmcnt(15)
	ds_write_b128 v180, v[174:177] offset:56320
	buffer_load_dwordx4 v[174:177], v0, s[84:87], s71 offen
	s_waitcnt lgkmcnt(0)
	s_barrier
	s_setprio 1
	ds_read_b128 v[202:205], v184 offset:40960
	ds_read_b128 v[206:209], v184 offset:43520
	ds_read_b128 v[214:217], v184 offset:46080
	ds_read_b128 v[218:221], v184 offset:48640
	ds_read_b128 v[210:213], v185
	ds_read_b128 v[222:225], v185 offset:2560
	s_waitcnt lgkmcnt(1)
	v_mfma_f32_16x16x32_bf16 v[126:129], v[202:205], v[210:213], v[126:129]
	v_mfma_f32_16x16x32_bf16 v[122:125], v[206:209], v[210:213], v[122:125]
	v_mfma_f32_16x16x32_bf16 v[118:121], v[214:217], v[210:213], v[118:121]
	v_mfma_f32_16x16x32_bf16 v[114:117], v[218:221], v[210:213], v[114:117]
	ds_read_b128 v[210:213], v185 offset:5120
	s_waitcnt lgkmcnt(1)
	v_mfma_f32_16x16x32_bf16 v[110:113], v[202:205], v[222:225], v[110:113]
	v_mfma_f32_16x16x32_bf16 v[106:109], v[206:209], v[222:225], v[106:109]
	v_mfma_f32_16x16x32_bf16 v[102:105], v[214:217], v[222:225], v[102:105]
	v_mfma_f32_16x16x32_bf16 v[98:101], v[218:221], v[222:225], v[98:101]
	ds_read_b128 v[222:225], v185 offset:7680
	ds_read_b128 v[226:229], v184 offset:41024
	ds_read_b128 v[230:233], v184 offset:43584
	ds_read_b128 v[234:237], v184 offset:46144
	ds_read_b128 v[238:241], v184 offset:48704
	ds_read_b128 v[242:245], v185 offset:64
	ds_read_b128 v[246:249], v185 offset:2624
	s_waitcnt lgkmcnt(7)
	v_mfma_f32_16x16x32_bf16 v[94:97], v[202:205], v[210:213], v[94:97]
	v_mfma_f32_16x16x32_bf16 v[90:93], v[206:209], v[210:213], v[90:93]
	v_mfma_f32_16x16x32_bf16 v[86:89], v[214:217], v[210:213], v[86:89]
	v_mfma_f32_16x16x32_bf16 v[82:85], v[218:221], v[210:213], v[82:85]
	s_waitcnt lgkmcnt(6)
	v_mfma_f32_16x16x32_bf16 v[78:81], v[202:205], v[222:225], v[78:81]
	v_mfma_f32_16x16x32_bf16 v[74:77], v[206:209], v[222:225], v[74:77]
	v_mfma_f32_16x16x32_bf16 v[70:73], v[214:217], v[222:225], v[70:73]
	v_mfma_f32_16x16x32_bf16 v[66:69], v[218:221], v[222:225], v[66:69]
	s_waitcnt lgkmcnt(1)
	v_mfma_f32_16x16x32_bf16 v[126:129], v[226:229], v[242:245], v[126:129]
	v_mfma_f32_16x16x32_bf16 v[122:125], v[230:233], v[242:245], v[122:125]
	v_mfma_f32_16x16x32_bf16 v[118:121], v[234:237], v[242:245], v[118:121]
	v_mfma_f32_16x16x32_bf16 v[114:117], v[238:241], v[242:245], v[114:117]
	ds_read_b128 v[202:205], v185 offset:5184
	s_waitcnt lgkmcnt(1)
	v_mfma_f32_16x16x32_bf16 v[110:113], v[226:229], v[246:249], v[110:113]
	v_mfma_f32_16x16x32_bf16 v[106:109], v[230:233], v[246:249], v[106:109]
	v_mfma_f32_16x16x32_bf16 v[102:105], v[234:237], v[246:249], v[102:105]
	v_mfma_f32_16x16x32_bf16 v[98:101], v[238:241], v[246:249], v[98:101]
	ds_read_b128 v[206:209], v185 offset:7744
	s_waitcnt lgkmcnt(1)
	v_mfma_f32_16x16x32_bf16 v[94:97], v[226:229], v[202:205], v[94:97]
	v_mfma_f32_16x16x32_bf16 v[90:93], v[230:233], v[202:205], v[90:93]
	v_mfma_f32_16x16x32_bf16 v[86:89], v[234:237], v[202:205], v[86:89]
	v_mfma_f32_16x16x32_bf16 v[82:85], v[238:241], v[202:205], v[82:85]
	s_waitcnt lgkmcnt(0)
	v_mfma_f32_16x16x32_bf16 v[78:81], v[226:229], v[206:209], v[78:81]
	v_mfma_f32_16x16x32_bf16 v[74:77], v[230:233], v[206:209], v[74:77]
	v_mfma_f32_16x16x32_bf16 v[70:73], v[234:237], v[206:209], v[70:73]
	v_mfma_f32_16x16x32_bf16 v[66:69], v[238:241], v[206:209], v[66:69]
	s_setprio 0
	s_barrier
	s_waitcnt vmcnt(15)
	ds_write_b128 v180, v[134:137] offset:20480
	buffer_load_dwordx4 v[134:137], v0, s[64:67], s42 offen offset:128
	s_waitcnt vmcnt(15)
	ds_write_b128 v180, v[142:145] offset:25600
	buffer_load_dwordx4 v[142:145], v0, s[64:67], s43 offen offset:128
	s_waitcnt vmcnt(15)
	ds_write_b128 v180, v[154:157]
	buffer_load_dwordx4 v[154:157], v0, s[64:67], s46 offen offset:128
	s_waitcnt vmcnt(15)
	ds_write_b128 v180, v[158:161] offset:5120
	buffer_load_dwordx4 v[158:161], v0, s[64:67], s47 offen offset:128
	s_waitcnt vmcnt(15)
	ds_write_b128 v180, v[2:5] offset:40960
	buffer_load_dwordx4 v[2:5], v0, s[84:87], s46 offen offset:128
	s_waitcnt vmcnt(15)
	ds_write_b128 v180, v[6:9] offset:46080
	buffer_load_dwordx4 v[6:9], v0, s[84:87], s47 offen offset:128
	s_waitcnt vmcnt(15)
	ds_write_b128 v180, v[10:13] offset:51200
	buffer_load_dwordx4 v[10:13], v0, s[84:87], s70 offen offset:128
	s_waitcnt vmcnt(15)
	ds_write_b128 v180, v[14:17] offset:56320
	buffer_load_dwordx4 v[14:17], v0, s[84:87], s71 offen offset:128
	s_waitcnt lgkmcnt(0)
	s_barrier
; template <bool VT>
; DI void gemm_mainloop(f32x4 (&acc)[8][4], const char* abase, const char* bbase, unsigned toff, u16* sA, u16* sB, int loff, int wm, int wn, int fr, int fq) {
;     ...
;   for (int kt = 0; kt < 16; ++kt) {
;     __syncthreads();
; #pragma unroll
;     for (int i = 0; i < 8; ++i) *(u32x4*)(sA + loff + i * 32 * GSTR) = ra[i];
; #pragma unroll
;     for (int i = 0; i < 4; ++i) *(u32x4*)(sB + loff + i * 32 * GSTR) = rb[i];
;     __syncthreads();
;     if (kt + 1 < 16) {
;       const int ko = (kt + 1) * 128;
; #pragma unroll
;       for (int i = 0; i < 8; ++i) ra[i] = __builtin_amdgcn_raw_buffer_load_b128(ra_rs, (int)toff, i * 65536 + ko, 0);
; #pragma unroll
;       for (int i = 0; i < 4; ++i) rb[i] = __builtin_amdgcn_raw_buffer_load_b128(rb_rs, (int)toff, i * 65536 + ko, 0);
;     }
;     __builtin_amdgcn_s_setprio(1);
;     gemm_kslab<VT>(acc, sA, sB, wm, wn, fr, fq);
;     __builtin_amdgcn_s_setprio(0);
	s_setprio 1
	ds_read_b128 v[202:205], v184 offset:40960
	ds_read_b128 v[206:209], v184 offset:43520
	ds_read_b128 v[214:217], v184 offset:46080
	ds_read_b128 v[218:221], v184 offset:48640
	ds_read_b128 v[210:213], v185
	ds_read_b128 v[222:225], v185 offset:2560
	s_waitcnt lgkmcnt(1)
	v_mfma_f32_16x16x32_bf16 v[126:129], v[202:205], v[210:213], v[126:129]
	v_mfma_f32_16x16x32_bf16 v[122:125], v[206:209], v[210:213], v[122:125]
	v_mfma_f32_16x16x32_bf16 v[118:121], v[214:217], v[210:213], v[118:121]
	v_mfma_f32_16x16x32_bf16 v[114:117], v[218:221], v[210:213], v[114:117]
	ds_read_b128 v[210:213], v185 offset:5120
	s_waitcnt lgkmcnt(1)
	v_mfma_f32_16x16x32_bf16 v[110:113], v[202:205], v[222:225], v[110:113]
	v_mfma_f32_16x16x32_bf16 v[106:109], v[206:209], v[222:225], v[106:109]
	v_mfma_f32_16x16x32_bf16 v[102:105], v[214:217], v[222:225], v[102:105]
	v_mfma_f32_16x16x32_bf16 v[98:101], v[218:221], v[222:225], v[98:101]
	ds_read_b128 v[222:225], v185 offset:7680
	ds_read_b128 v[226:229], v184 offset:41024
	ds_read_b128 v[230:233], v184 offset:43584
	ds_read_b128 v[234:237], v184 offset:46144
	ds_read_b128 v[238:241], v184 offset:48704
	ds_read_b128 v[242:245], v185 offset:64
	ds_read_b128 v[246:249], v185 offset:2624
	s_waitcnt lgkmcnt(7)
	v_mfma_f32_16x16x32_bf16 v[94:97], v[202:205], v[210:213], v[94:97]
	v_mfma_f32_16x16x32_bf16 v[90:93], v[206:209], v[210:213], v[90:93]
	v_mfma_f32_16x16x32_bf16 v[86:89], v[214:217], v[210:213], v[86:89]
	v_mfma_f32_16x16x32_bf16 v[82:85], v[218:221], v[210:213], v[82:85]
	s_waitcnt lgkmcnt(6)
	v_mfma_f32_16x16x32_bf16 v[78:81], v[202:205], v[222:225], v[78:81]
	v_mfma_f32_16x16x32_bf16 v[74:77], v[206:209], v[222:225], v[74:77]
	v_mfma_f32_16x16x32_bf16 v[70:73], v[214:217], v[222:225], v[70:73]
	v_mfma_f32_16x16x32_bf16 v[66:69], v[218:221], v[222:225], v[66:69]
	s_waitcnt lgkmcnt(1)
	v_mfma_f32_16x16x32_bf16 v[126:129], v[226:229], v[242:245], v[126:129]
	v_mfma_f32_16x16x32_bf16 v[122:125], v[230:233], v[242:245], v[122:125]
	v_mfma_f32_16x16x32_bf16 v[118:121], v[234:237], v[242:245], v[118:121]
	v_mfma_f32_16x16x32_bf16 v[114:117], v[238:241], v[242:245], v[114:117]
	ds_read_b128 v[202:205], v185 offset:5184
	s_waitcnt lgkmcnt(1)
	v_mfma_f32_16x16x32_bf16 v[110:113], v[226:229], v[246:249], v[110:113]
	v_mfma_f32_16x16x32_bf16 v[106:109], v[230:233], v[246:249], v[106:109]
	v_mfma_f32_16x16x32_bf16 v[102:105], v[234:237], v[246:249], v[102:105]
	v_mfma_f32_16x16x32_bf16 v[98:101], v[238:241], v[246:249], v[98:101]
	ds_read_b128 v[206:209], v185 offset:7744
	s_waitcnt lgkmcnt(1)
	v_mfma_f32_16x16x32_bf16 v[94:97], v[226:229], v[202:205], v[94:97]
	v_mfma_f32_16x16x32_bf16 v[90:93], v[230:233], v[202:205], v[90:93]
	v_mfma_f32_16x16x32_bf16 v[86:89], v[234:237], v[202:205], v[86:89]
	v_mfma_f32_16x16x32_bf16 v[82:85], v[238:241], v[202:205], v[82:85]
	s_waitcnt lgkmcnt(0)
	v_mfma_f32_16x16x32_bf16 v[78:81], v[226:229], v[206:209], v[78:81]
	v_mfma_f32_16x16x32_bf16 v[74:77], v[230:233], v[206:209], v[74:77]
	v_mfma_f32_16x16x32_bf16 v[70:73], v[234:237], v[206:209], v[70:73]
	v_mfma_f32_16x16x32_bf16 v[66:69], v[238:241], v[206:209], v[66:69]
	s_setprio 0
	s_sub_i32 s32, s32, 1
	s_cmp_lg_u32 s32, 0
	s_cbranch_scc1 .Lh0_loop
	s_barrier
	s_waitcnt vmcnt(15)
	ds_write_b128 v180, v[146:149] offset:20480
	s_waitcnt vmcnt(14)
	ds_write_b128 v180, v[150:153] offset:25600
	s_waitcnt vmcnt(13)
	ds_write_b128 v180, v[130:133]
	s_waitcnt vmcnt(12)
	ds_write_b128 v180, v[138:141] offset:5120
	s_waitcnt vmcnt(11)
	ds_write_b128 v180, v[162:165] offset:40960
	s_waitcnt vmcnt(10)
	ds_write_b128 v180, v[170:173] offset:46080
	s_waitcnt vmcnt(9)
	ds_write_b128 v180, v[166:169] offset:51200
	s_waitcnt vmcnt(8)
	ds_write_b128 v180, v[174:177] offset:56320
	s_waitcnt lgkmcnt(0)
	s_barrier
; template <bool VT>
; DI void gemm_mainloop(f32x4 (&acc)[8][4], const char* abase, const char* bbase, unsigned toff, u16* sA, u16* sB, int loff, int wm, int wn, int fr, int fq) {
;     ...
;   for (int kt = 0; kt < 16; ++kt) {
;     __syncthreads();
; #pragma unroll
;     for (int i = 0; i < 8; ++i) *(u32x4*)(sA + loff + i * 32 * GSTR) = ra[i];
; #pragma unroll
;     for (int i = 0; i < 4; ++i) *(u32x4*)(sB + loff + i * 32 * GSTR) = rb[i];
;     __syncthreads();
;     if (kt + 1 < 16) {
;       const int ko = (kt + 1) * 128;
; #pragma unroll
;       for (int i = 0; i < 8; ++i) ra[i] = __builtin_amdgcn_raw_buffer_load_b128(ra_rs, (int)toff, i * 65536 + ko, 0);
; #pragma unroll
;       for (int i = 0; i < 4; ++i) rb[i] = __builtin_amdgcn_raw_buffer_load_b128(rb_rs, (int)toff, i * 65536 + ko, 0);
;     }
;     __builtin_amdgcn_s_setprio(1);
;     gemm_kslab<VT>(acc, sA, sB, wm, wn, fr, fq);
;     __builtin_amdgcn_s_setprio(0);
	s_setprio 1
	ds_read_b128 v[202:205], v184 offset:40960
	ds_read_b128 v[206:209], v184 offset:43520
	ds_read_b128 v[214:217], v184 offset:46080
	ds_read_b128 v[218:221], v184 offset:48640
	ds_read_b128 v[210:213], v185
	ds_read_b128 v[222:225], v185 offset:2560
	s_waitcnt lgkmcnt(1)
	v_mfma_f32_16x16x32_bf16 v[126:129], v[202:205], v[210:213], v[126:129]
	v_mfma_f32_16x16x32_bf16 v[122:125], v[206:209], v[210:213], v[122:125]
	v_mfma_f32_16x16x32_bf16 v[118:121], v[214:217], v[210:213], v[118:121]
	v_mfma_f32_16x16x32_bf16 v[114:117], v[218:221], v[210:213], v[114:117]
	ds_read_b128 v[210:213], v185 offset:5120
	s_waitcnt lgkmcnt(1)
	v_mfma_f32_16x16x32_bf16 v[110:113], v[202:205], v[222:225], v[110:113]
	v_mfma_f32_16x16x32_bf16 v[106:109], v[206:209], v[222:225], v[106:109]
	v_mfma_f32_16x16x32_bf16 v[102:105], v[214:217], v[222:225], v[102:105]
	v_mfma_f32_16x16x32_bf16 v[98:101], v[218:221], v[222:225], v[98:101]
	ds_read_b128 v[222:225], v185 offset:7680
	ds_read_b128 v[226:229], v184 offset:41024
	ds_read_b128 v[230:233], v184 offset:43584
	ds_read_b128 v[234:237], v184 offset:46144
	ds_read_b128 v[238:241], v184 offset:48704
	ds_read_b128 v[242:245], v185 offset:64
	ds_read_b128 v[246:249], v185 offset:2624
	s_waitcnt lgkmcnt(7)
	v_mfma_f32_16x16x32_bf16 v[94:97], v[202:205], v[210:213], v[94:97]
	v_mfma_f32_16x16x32_bf16 v[90:93], v[206:209], v[210:213], v[90:93]
	v_mfma_f32_16x16x32_bf16 v[86:89], v[214:217], v[210:213], v[86:89]
	v_mfma_f32_16x16x32_bf16 v[82:85], v[218:221], v[210:213], v[82:85]
	s_waitcnt lgkmcnt(6)
	v_mfma_f32_16x16x32_bf16 v[78:81], v[202:205], v[222:225], v[78:81]
	v_mfma_f32_16x16x32_bf16 v[74:77], v[206:209], v[222:225], v[74:77]
	v_mfma_f32_16x16x32_bf16 v[70:73], v[214:217], v[222:225], v[70:73]
	v_mfma_f32_16x16x32_bf16 v[66:69], v[218:221], v[222:225], v[66:69]
	s_waitcnt lgkmcnt(1)
	v_mfma_f32_16x16x32_bf16 v[126:129], v[226:229], v[242:245], v[126:129]
	v_mfma_f32_16x16x32_bf16 v[122:125], v[230:233], v[242:245], v[122:125]
	v_mfma_f32_16x16x32_bf16 v[118:121], v[234:237], v[242:245], v[118:121]
	v_mfma_f32_16x16x32_bf16 v[114:117], v[238:241], v[242:245], v[114:117]
	ds_read_b128 v[202:205], v185 offset:5184
	s_waitcnt lgkmcnt(1)
	v_mfma_f32_16x16x32_bf16 v[110:113], v[226:229], v[246:249], v[110:113]
	v_mfma_f32_16x16x32_bf16 v[106:109], v[230:233], v[246:249], v[106:109]
	v_mfma_f32_16x16x32_bf16 v[102:105], v[234:237], v[246:249], v[102:105]
	v_mfma_f32_16x16x32_bf16 v[98:101], v[238:241], v[246:249], v[98:101]
	ds_read_b128 v[206:209], v185 offset:7744
	s_waitcnt lgkmcnt(1)
	v_mfma_f32_16x16x32_bf16 v[94:97], v[226:229], v[202:205], v[94:97]
	v_mfma_f32_16x16x32_bf16 v[90:93], v[230:233], v[202:205], v[90:93]
	v_mfma_f32_16x16x32_bf16 v[86:89], v[234:237], v[202:205], v[86:89]
	v_mfma_f32_16x16x32_bf16 v[82:85], v[238:241], v[202:205], v[82:85]
	s_waitcnt lgkmcnt(0)
	v_mfma_f32_16x16x32_bf16 v[78:81], v[226:229], v[206:209], v[78:81]
	v_mfma_f32_16x16x32_bf16 v[74:77], v[230:233], v[206:209], v[74:77]
	v_mfma_f32_16x16x32_bf16 v[70:73], v[234:237], v[206:209], v[70:73]
	v_mfma_f32_16x16x32_bf16 v[66:69], v[238:241], v[206:209], v[66:69]
	s_setprio 0
	s_barrier
	s_waitcnt vmcnt(7)
	ds_write_b128 v180, v[134:137] offset:20480
	s_waitcnt vmcnt(6)
	ds_write_b128 v180, v[142:145] offset:25600
	s_waitcnt vmcnt(5)
	ds_write_b128 v180, v[154:157]
	s_waitcnt vmcnt(4)
	ds_write_b128 v180, v[158:161] offset:5120
	s_waitcnt vmcnt(3)
	ds_write_b128 v180, v[2:5] offset:40960
	s_waitcnt vmcnt(2)
	ds_write_b128 v180, v[6:9] offset:46080
	s_waitcnt vmcnt(1)
	ds_write_b128 v180, v[10:13] offset:51200
	s_waitcnt vmcnt(0)
	ds_write_b128 v180, v[14:17] offset:56320
	s_waitcnt lgkmcnt(0)
	s_barrier
	s_setprio 1
	ds_read_b128 v[202:205], v184 offset:40960
	ds_read_b128 v[206:209], v184 offset:43520
	ds_read_b128 v[214:217], v184 offset:46080
	ds_read_b128 v[218:221], v184 offset:48640
	ds_read_b128 v[210:213], v185
	ds_read_b128 v[222:225], v185 offset:2560
	s_waitcnt lgkmcnt(1)
	v_mfma_f32_16x16x32_bf16 v[126:129], v[202:205], v[210:213], v[126:129]
	v_mfma_f32_16x16x32_bf16 v[122:125], v[206:209], v[210:213], v[122:125]
	v_mfma_f32_16x16x32_bf16 v[118:121], v[214:217], v[210:213], v[118:121]
	v_mfma_f32_16x16x32_bf16 v[114:117], v[218:221], v[210:213], v[114:117]
	ds_read_b128 v[210:213], v185 offset:5120
	s_waitcnt lgkmcnt(1)
	v_mfma_f32_16x16x32_bf16 v[110:113], v[202:205], v[222:225], v[110:113]
	v_mfma_f32_16x16x32_bf16 v[106:109], v[206:209], v[222:225], v[106:109]
	v_mfma_f32_16x16x32_bf16 v[102:105], v[214:217], v[222:225], v[102:105]
	v_mfma_f32_16x16x32_bf16 v[98:101], v[218:221], v[222:225], v[98:101]
	ds_read_b128 v[222:225], v185 offset:7680
	ds_read_b128 v[226:229], v184 offset:41024
	ds_read_b128 v[230:233], v184 offset:43584
	ds_read_b128 v[234:237], v184 offset:46144
	ds_read_b128 v[238:241], v184 offset:48704
	ds_read_b128 v[242:245], v185 offset:64
	ds_read_b128 v[246:249], v185 offset:2624
	s_waitcnt lgkmcnt(7)
	v_mfma_f32_16x16x32_bf16 v[94:97], v[202:205], v[210:213], v[94:97]
	v_mfma_f32_16x16x32_bf16 v[90:93], v[206:209], v[210:213], v[90:93]
	v_mfma_f32_16x16x32_bf16 v[86:89], v[214:217], v[210:213], v[86:89]
	v_mfma_f32_16x16x32_bf16 v[82:85], v[218:221], v[210:213], v[82:85]
	s_waitcnt lgkmcnt(6)
	v_mfma_f32_16x16x32_bf16 v[78:81], v[202:205], v[222:225], v[78:81]
	v_mfma_f32_16x16x32_bf16 v[74:77], v[206:209], v[222:225], v[74:77]
	v_mfma_f32_16x16x32_bf16 v[70:73], v[214:217], v[222:225], v[70:73]
	v_mfma_f32_16x16x32_bf16 v[66:69], v[218:221], v[222:225], v[66:69]
	s_waitcnt lgkmcnt(1)
	v_mfma_f32_16x16x32_bf16 v[126:129], v[226:229], v[242:245], v[126:129]
	v_mfma_f32_16x16x32_bf16 v[122:125], v[230:233], v[242:245], v[122:125]
	v_mfma_f32_16x16x32_bf16 v[118:121], v[234:237], v[242:245], v[118:121]
	v_mfma_f32_16x16x32_bf16 v[114:117], v[238:241], v[242:245], v[114:117]
	ds_read_b128 v[202:205], v185 offset:5184
	s_waitcnt lgkmcnt(1)
	v_mfma_f32_16x16x32_bf16 v[110:113], v[226:229], v[246:249], v[110:113]
	v_mfma_f32_16x16x32_bf16 v[106:109], v[230:233], v[246:249], v[106:109]
	v_mfma_f32_16x16x32_bf16 v[102:105], v[234:237], v[246:249], v[102:105]
	v_mfma_f32_16x16x32_bf16 v[98:101], v[238:241], v[246:249], v[98:101]
	ds_read_b128 v[206:209], v185 offset:7744
	s_waitcnt lgkmcnt(1)
	v_mfma_f32_16x16x32_bf16 v[94:97], v[226:229], v[202:205], v[94:97]
	v_mfma_f32_16x16x32_bf16 v[90:93], v[230:233], v[202:205], v[90:93]
	v_mfma_f32_16x16x32_bf16 v[86:89], v[234:237], v[202:205], v[86:89]
	v_mfma_f32_16x16x32_bf16 v[82:85], v[238:241], v[202:205], v[82:85]
	s_waitcnt lgkmcnt(0)
	v_mfma_f32_16x16x32_bf16 v[78:81], v[226:229], v[206:209], v[78:81]
	v_mfma_f32_16x16x32_bf16 v[74:77], v[230:233], v[206:209], v[74:77]
	v_mfma_f32_16x16x32_bf16 v[70:73], v[234:237], v[206:209], v[70:73]
	v_mfma_f32_16x16x32_bf16 v[66:69], v[238:241], v[206:209], v[66:69]
	s_setprio 0
	s_branch .LBB0_118

; template <bool VT>
; DI void gemm_mainloop(f32x4 (&acc)[8][4], const char* abase, const char* bbase, unsigned toff, u16* sA, u16* sB, int loff, int wm, int wn, int fr, int fq) {
;     ...
;   for (int kt = 0; kt < 16; ++kt) {
;     __syncthreads();
; #pragma unroll
;     for (int i = 0; i < 8; ++i) *(u32x4*)(sA + loff + i * 32 * GSTR) = ra[i];
; #pragma unroll
;     for (int i = 0; i < 4; ++i) *(u32x4*)(sB + loff + i * 32 * GSTR) = rb[i];
;     __syncthreads();
;     if (kt + 1 < 16) {
;       const int ko = (kt + 1) * 128;
; #pragma unroll
;       for (int i = 0; i < 8; ++i) ra[i] = __builtin_amdgcn_raw_buffer_load_b128(ra_rs, (int)toff, i * 65536 + ko, 0);
; #pragma unroll
;       for (int i = 0; i < 4; ++i) rb[i] = __builtin_amdgcn_raw_buffer_load_b128(rb_rs, (int)toff, i * 65536 + ko, 0);
;     }
;     __builtin_amdgcn_s_setprio(1);
;     gemm_kslab<VT>(acc, sA, sB, wm, wn, fr, fq);
;     __builtin_amdgcn_s_setprio(0);
.Lh1_loop:
	s_barrier
	s_addk_i32 s42, 0x100
	s_addk_i32 s43, 0x100
	s_addk_i32 s46, 0x100
	s_addk_i32 s47, 0x100
	s_addk_i32 s70, 0x100
	s_addk_i32 s71, 0x100
	s_waitcnt vmcnt(15)
	ds_write_b128 v180, v[134:137] offset:10240
	buffer_load_dwordx4 v[134:137], v0, s[64:67], s42 offen
	s_waitcnt vmcnt(15)
	ds_write_b128 v180, v[142:145] offset:15360
	buffer_load_dwordx4 v[142:145], v0, s[64:67], s43 offen
	s_waitcnt vmcnt(15)
	ds_write_b128 v180, v[154:157] offset:30720
	buffer_load_dwordx4 v[154:157], v0, s[64:67], s46 offen
	s_waitcnt vmcnt(15)
	ds_write_b128 v180, v[158:161] offset:35840
	buffer_load_dwordx4 v[158:161], v0, s[64:67], s47 offen
	s_waitcnt vmcnt(15)
	ds_write_b128 v180, v[162:165] offset:40960
	buffer_load_dwordx4 v[162:165], v0, s[84:87], s70 offen
	s_waitcnt vmcnt(15)
	ds_write_b128 v180, v[170:173] offset:46080
	buffer_load_dwordx4 v[170:173], v0, s[84:87], s71 offen
	s_waitcnt vmcnt(15)
	ds_write_b128 v180, v[166:169] offset:51200
	buffer_load_dwordx4 v[166:169], v0, s[84:87], s42 offen
	s_waitcnt vmcnt(15)
	ds_write_b128 v180, v[174:177] offset:56320
	buffer_load_dwordx4 v[174:177], v0, s[84:87], s43 offen
	s_waitcnt lgkmcnt(0)
	s_barrier
	s_setprio 1
	ds_read_b128 v[202:205], v184 offset:40960
	ds_read_b128 v[206:209], v184 offset:43520
	ds_read_b128 v[214:217], v184 offset:46080
	ds_read_b128 v[218:221], v184 offset:48640
	ds_read_b128 v[210:213], v185 offset:10240
	ds_read_b128 v[222:225], v185 offset:12800
	s_waitcnt lgkmcnt(1)
	v_mfma_f32_16x16x32_bf16 v[62:65], v[202:205], v[210:213], v[62:65]
	v_mfma_f32_16x16x32_bf16 v[58:61], v[206:209], v[210:213], v[58:61]
	v_mfma_f32_16x16x32_bf16 v[54:57], v[214:217], v[210:213], v[54:57]
	v_mfma_f32_16x16x32_bf16 v[50:53], v[218:221], v[210:213], v[50:53]
	ds_read_b128 v[210:213], v185 offset:15360
	s_waitcnt lgkmcnt(1)
	v_mfma_f32_16x16x32_bf16 v[46:49], v[202:205], v[222:225], v[46:49]
	v_mfma_f32_16x16x32_bf16 v[42:45], v[206:209], v[222:225], v[42:45]
	v_mfma_f32_16x16x32_bf16 v[38:41], v[214:217], v[222:225], v[38:41]
	v_mfma_f32_16x16x32_bf16 v[34:37], v[218:221], v[222:225], v[34:37]
	ds_read_b128 v[222:225], v185 offset:17920
	ds_read_b128 v[226:229], v184 offset:41024
	ds_read_b128 v[230:233], v184 offset:43584
	ds_read_b128 v[234:237], v184 offset:46144
	ds_read_b128 v[238:241], v184 offset:48704
	ds_read_b128 v[242:245], v185 offset:10304
	ds_read_b128 v[246:249], v185 offset:12864
	s_waitcnt lgkmcnt(7)
	v_mfma_f32_16x16x32_bf16 v[30:33], v[202:205], v[210:213], v[30:33]
	v_mfma_f32_16x16x32_bf16 v[26:29], v[206:209], v[210:213], v[26:29]
	v_mfma_f32_16x16x32_bf16 v[22:25], v[214:217], v[210:213], v[22:25]
	v_mfma_f32_16x16x32_bf16 v[18:21], v[218:221], v[210:213], v[18:21]
	s_waitcnt lgkmcnt(6)
	v_mfma_f32_16x16x32_bf16 v[14:17], v[202:205], v[222:225], v[14:17]
	v_mfma_f32_16x16x32_bf16 v[6:9], v[206:209], v[222:225], v[6:9]
	v_mfma_f32_16x16x32_bf16 v[2:5], v[214:217], v[222:225], v[2:5]
	v_mfma_f32_16x16x32_bf16 v[10:13], v[218:221], v[222:225], v[10:13]
	s_waitcnt lgkmcnt(1)
	v_mfma_f32_16x16x32_bf16 v[62:65], v[226:229], v[242:245], v[62:65]
	v_mfma_f32_16x16x32_bf16 v[58:61], v[230:233], v[242:245], v[58:61]
	v_mfma_f32_16x16x32_bf16 v[54:57], v[234:237], v[242:245], v[54:57]
	v_mfma_f32_16x16x32_bf16 v[50:53], v[238:241], v[242:245], v[50:53]
	ds_read_b128 v[202:205], v185 offset:15424
	s_waitcnt lgkmcnt(1)
	v_mfma_f32_16x16x32_bf16 v[46:49], v[226:229], v[246:249], v[46:49]
	v_mfma_f32_16x16x32_bf16 v[42:45], v[230:233], v[246:249], v[42:45]
	v_mfma_f32_16x16x32_bf16 v[38:41], v[234:237], v[246:249], v[38:41]
	v_mfma_f32_16x16x32_bf16 v[34:37], v[238:241], v[246:249], v[34:37]
	ds_read_b128 v[206:209], v185 offset:17984
	s_waitcnt lgkmcnt(1)
	v_mfma_f32_16x16x32_bf16 v[30:33], v[226:229], v[202:205], v[30:33]
	v_mfma_f32_16x16x32_bf16 v[26:29], v[230:233], v[202:205], v[26:29]
	v_mfma_f32_16x16x32_bf16 v[22:25], v[234:237], v[202:205], v[22:25]
	v_mfma_f32_16x16x32_bf16 v[18:21], v[238:241], v[202:205], v[18:21]
	s_waitcnt lgkmcnt(0)
	v_mfma_f32_16x16x32_bf16 v[14:17], v[226:229], v[206:209], v[14:17]
	v_mfma_f32_16x16x32_bf16 v[6:9], v[230:233], v[206:209], v[6:9]
	v_mfma_f32_16x16x32_bf16 v[2:5], v[234:237], v[206:209], v[2:5]
	v_mfma_f32_16x16x32_bf16 v[10:13], v[238:241], v[206:209], v[10:13]
	s_setprio 0
	s_barrier
	s_waitcnt vmcnt(15)
	ds_write_b128 v180, v[130:133] offset:10240
	buffer_load_dwordx4 v[130:133], v0, s[64:67], s42 offen offset:128
	s_waitcnt vmcnt(15)
	ds_write_b128 v180, v[138:141] offset:15360
	buffer_load_dwordx4 v[138:141], v0, s[64:67], s43 offen offset:128
	s_waitcnt vmcnt(15)
	ds_write_b128 v180, v[146:149] offset:30720
	buffer_load_dwordx4 v[146:149], v0, s[64:67], s46 offen offset:128
	s_waitcnt vmcnt(15)
	ds_write_b128 v180, v[150:153] offset:35840
	buffer_load_dwordx4 v[150:153], v0, s[64:67], s47 offen offset:128
	s_waitcnt vmcnt(15)
	ds_write_b128 v180, v[66:69] offset:40960
	buffer_load_dwordx4 v[66:69], v0, s[84:87], s70 offen offset:128
	s_waitcnt vmcnt(15)
	ds_write_b128 v180, v[70:73] offset:46080
	buffer_load_dwordx4 v[70:73], v0, s[84:87], s71 offen offset:128
	s_waitcnt vmcnt(15)
	ds_write_b128 v180, v[74:77] offset:51200
	buffer_load_dwordx4 v[74:77], v0, s[84:87], s42 offen offset:128
	s_waitcnt vmcnt(15)
	ds_write_b128 v180, v[78:81] offset:56320
	buffer_load_dwordx4 v[78:81], v0, s[84:87], s43 offen offset:128
	s_waitcnt lgkmcnt(0)
	s_barrier
; template <bool VT>
; DI void gemm_mainloop(f32x4 (&acc)[8][4], const char* abase, const char* bbase, unsigned toff, u16* sA, u16* sB, int loff, int wm, int wn, int fr, int fq) {
;     ...
;   for (int kt = 0; kt < 16; ++kt) {
;     __syncthreads();
; #pragma unroll
;     for (int i = 0; i < 8; ++i) *(u32x4*)(sA + loff + i * 32 * GSTR) = ra[i];
; #pragma unroll
;     for (int i = 0; i < 4; ++i) *(u32x4*)(sB + loff + i * 32 * GSTR) = rb[i];
;     __syncthreads();
;     if (kt + 1 < 16) {
;       const int ko = (kt + 1) * 128;
; #pragma unroll
;       for (int i = 0; i < 8; ++i) ra[i] = __builtin_amdgcn_raw_buffer_load_b128(ra_rs, (int)toff, i * 65536 + ko, 0);
; #pragma unroll
;       for (int i = 0; i < 4; ++i) rb[i] = __builtin_amdgcn_raw_buffer_load_b128(rb_rs, (int)toff, i * 65536 + ko, 0);
;     }
;     __builtin_amdgcn_s_setprio(1);
;     gemm_kslab<VT>(acc, sA, sB, wm, wn, fr, fq);
;     __builtin_amdgcn_s_setprio(0);
	s_setprio 1
	ds_read_b128 v[202:205], v184 offset:40960
	ds_read_b128 v[206:209], v184 offset:43520
	ds_read_b128 v[214:217], v184 offset:46080
	ds_read_b128 v[218:221], v184 offset:48640
	ds_read_b128 v[210:213], v185 offset:10240
	ds_read_b128 v[222:225], v185 offset:12800
	s_waitcnt lgkmcnt(1)
	v_mfma_f32_16x16x32_bf16 v[62:65], v[202:205], v[210:213], v[62:65]
	v_mfma_f32_16x16x32_bf16 v[58:61], v[206:209], v[210:213], v[58:61]
	v_mfma_f32_16x16x32_bf16 v[54:57], v[214:217], v[210:213], v[54:57]
	v_mfma_f32_16x16x32_bf16 v[50:53], v[218:221], v[210:213], v[50:53]
	ds_read_b128 v[210:213], v185 offset:15360
	s_waitcnt lgkmcnt(1)
	v_mfma_f32_16x16x32_bf16 v[46:49], v[202:205], v[222:225], v[46:49]
	v_mfma_f32_16x16x32_bf16 v[42:45], v[206:209], v[222:225], v[42:45]
	v_mfma_f32_16x16x32_bf16 v[38:41], v[214:217], v[222:225], v[38:41]
	v_mfma_f32_16x16x32_bf16 v[34:37], v[218:221], v[222:225], v[34:37]
	ds_read_b128 v[222:225], v185 offset:17920
	ds_read_b128 v[226:229], v184 offset:41024
	ds_read_b128 v[230:233], v184 offset:43584
	ds_read_b128 v[234:237], v184 offset:46144
	ds_read_b128 v[238:241], v184 offset:48704
	ds_read_b128 v[242:245], v185 offset:10304
	ds_read_b128 v[246:249], v185 offset:12864
	s_waitcnt lgkmcnt(7)
	v_mfma_f32_16x16x32_bf16 v[30:33], v[202:205], v[210:213], v[30:33]
	v_mfma_f32_16x16x32_bf16 v[26:29], v[206:209], v[210:213], v[26:29]
	v_mfma_f32_16x16x32_bf16 v[22:25], v[214:217], v[210:213], v[22:25]
	v_mfma_f32_16x16x32_bf16 v[18:21], v[218:221], v[210:213], v[18:21]
	s_waitcnt lgkmcnt(6)
	v_mfma_f32_16x16x32_bf16 v[14:17], v[202:205], v[222:225], v[14:17]
	v_mfma_f32_16x16x32_bf16 v[6:9], v[206:209], v[222:225], v[6:9]
	v_mfma_f32_16x16x32_bf16 v[2:5], v[214:217], v[222:225], v[2:5]
	v_mfma_f32_16x16x32_bf16 v[10:13], v[218:221], v[222:225], v[10:13]
	s_waitcnt lgkmcnt(1)
	v_mfma_f32_16x16x32_bf16 v[62:65], v[226:229], v[242:245], v[62:65]
	v_mfma_f32_16x16x32_bf16 v[58:61], v[230:233], v[242:245], v[58:61]
	v_mfma_f32_16x16x32_bf16 v[54:57], v[234:237], v[242:245], v[54:57]
	v_mfma_f32_16x16x32_bf16 v[50:53], v[238:241], v[242:245], v[50:53]
	ds_read_b128 v[202:205], v185 offset:15424
	s_waitcnt lgkmcnt(1)
	v_mfma_f32_16x16x32_bf16 v[46:49], v[226:229], v[246:249], v[46:49]
	v_mfma_f32_16x16x32_bf16 v[42:45], v[230:233], v[246:249], v[42:45]
	v_mfma_f32_16x16x32_bf16 v[38:41], v[234:237], v[246:249], v[38:41]
	v_mfma_f32_16x16x32_bf16 v[34:37], v[238:241], v[246:249], v[34:37]
	ds_read_b128 v[206:209], v185 offset:17984
	s_waitcnt lgkmcnt(1)
	v_mfma_f32_16x16x32_bf16 v[30:33], v[226:229], v[202:205], v[30:33]
	v_mfma_f32_16x16x32_bf16 v[26:29], v[230:233], v[202:205], v[26:29]
	v_mfma_f32_16x16x32_bf16 v[22:25], v[234:237], v[202:205], v[22:25]
	v_mfma_f32_16x16x32_bf16 v[18:21], v[238:241], v[202:205], v[18:21]
	s_waitcnt lgkmcnt(0)
	v_mfma_f32_16x16x32_bf16 v[14:17], v[226:229], v[206:209], v[14:17]
	v_mfma_f32_16x16x32_bf16 v[6:9], v[230:233], v[206:209], v[6:9]
	v_mfma_f32_16x16x32_bf16 v[2:5], v[234:237], v[206:209], v[2:5]
	v_mfma_f32_16x16x32_bf16 v[10:13], v[238:241], v[206:209], v[10:13]
	s_setprio 0
	s_sub_i32 s32, s32, 1
	s_cmp_lg_u32 s32, 0
	s_cbranch_scc1 .Lh1_loop
	s_barrier
	s_waitcnt vmcnt(15)
	ds_write_b128 v180, v[134:137] offset:10240
	s_waitcnt vmcnt(14)
	ds_write_b128 v180, v[142:145] offset:15360
	s_waitcnt vmcnt(13)
	ds_write_b128 v180, v[154:157] offset:30720
	s_waitcnt vmcnt(12)
	ds_write_b128 v180, v[158:161] offset:35840
	s_waitcnt vmcnt(11)
	ds_write_b128 v180, v[162:165] offset:40960
	s_waitcnt vmcnt(10)
	ds_write_b128 v180, v[170:173] offset:46080
	s_waitcnt vmcnt(9)
	ds_write_b128 v180, v[166:169] offset:51200
	s_waitcnt vmcnt(8)
	ds_write_b128 v180, v[174:177] offset:56320
	s_waitcnt lgkmcnt(0)
	s_barrier
; template <bool VT>
; DI void gemm_mainloop(f32x4 (&acc)[8][4], const char* abase, const char* bbase, unsigned toff, u16* sA, u16* sB, int loff, int wm, int wn, int fr, int fq) {
;     ...
;   for (int kt = 0; kt < 16; ++kt) {
;     __syncthreads();
; #pragma unroll
;     for (int i = 0; i < 8; ++i) *(u32x4*)(sA + loff + i * 32 * GSTR) = ra[i];
; #pragma unroll
;     for (int i = 0; i < 4; ++i) *(u32x4*)(sB + loff + i * 32 * GSTR) = rb[i];
;     __syncthreads();
;     if (kt + 1 < 16) {
;       const int ko = (kt + 1) * 128;
; #pragma unroll
;       for (int i = 0; i < 8; ++i) ra[i] = __builtin_amdgcn_raw_buffer_load_b128(ra_rs, (int)toff, i * 65536 + ko, 0);
; #pragma unroll
;       for (int i = 0; i < 4; ++i) rb[i] = __builtin_amdgcn_raw_buffer_load_b128(rb_rs, (int)toff, i * 65536 + ko, 0);
;     }
;     __builtin_amdgcn_s_setprio(1);
;     gemm_kslab<VT>(acc, sA, sB, wm, wn, fr, fq);
;     __builtin_amdgcn_s_setprio(0);
	s_setprio 1
	ds_read_b128 v[202:205], v184 offset:40960
	ds_read_b128 v[206:209], v184 offset:43520
	ds_read_b128 v[214:217], v184 offset:46080
	ds_read_b128 v[218:221], v184 offset:48640
	ds_read_b128 v[210:213], v185 offset:10240
	ds_read_b128 v[222:225], v185 offset:12800
	s_waitcnt lgkmcnt(1)
	v_mfma_f32_16x16x32_bf16 v[62:65], v[202:205], v[210:213], v[62:65]
	v_mfma_f32_16x16x32_bf16 v[58:61], v[206:209], v[210:213], v[58:61]
	v_mfma_f32_16x16x32_bf16 v[54:57], v[214:217], v[210:213], v[54:57]
	v_mfma_f32_16x16x32_bf16 v[50:53], v[218:221], v[210:213], v[50:53]
	ds_read_b128 v[210:213], v185 offset:15360
	s_waitcnt lgkmcnt(1)
	v_mfma_f32_16x16x32_bf16 v[46:49], v[202:205], v[222:225], v[46:49]
	v_mfma_f32_16x16x32_bf16 v[42:45], v[206:209], v[222:225], v[42:45]
	v_mfma_f32_16x16x32_bf16 v[38:41], v[214:217], v[222:225], v[38:41]
	v_mfma_f32_16x16x32_bf16 v[34:37], v[218:221], v[222:225], v[34:37]
	ds_read_b128 v[222:225], v185 offset:17920
	ds_read_b128 v[226:229], v184 offset:41024
	ds_read_b128 v[230:233], v184 offset:43584
	ds_read_b128 v[234:237], v184 offset:46144
	ds_read_b128 v[238:241], v184 offset:48704
	ds_read_b128 v[242:245], v185 offset:10304
	ds_read_b128 v[246:249], v185 offset:12864
	s_waitcnt lgkmcnt(7)
	v_mfma_f32_16x16x32_bf16 v[30:33], v[202:205], v[210:213], v[30:33]
	v_mfma_f32_16x16x32_bf16 v[26:29], v[206:209], v[210:213], v[26:29]
	v_mfma_f32_16x16x32_bf16 v[22:25], v[214:217], v[210:213], v[22:25]
	v_mfma_f32_16x16x32_bf16 v[18:21], v[218:221], v[210:213], v[18:21]
	s_waitcnt lgkmcnt(6)
	v_mfma_f32_16x16x32_bf16 v[14:17], v[202:205], v[222:225], v[14:17]
	v_mfma_f32_16x16x32_bf16 v[6:9], v[206:209], v[222:225], v[6:9]
	v_mfma_f32_16x16x32_bf16 v[2:5], v[214:217], v[222:225], v[2:5]
	v_mfma_f32_16x16x32_bf16 v[10:13], v[218:221], v[222:225], v[10:13]
	s_waitcnt lgkmcnt(1)
	v_mfma_f32_16x16x32_bf16 v[62:65], v[226:229], v[242:245], v[62:65]
	v_mfma_f32_16x16x32_bf16 v[58:61], v[230:233], v[242:245], v[58:61]
	v_mfma_f32_16x16x32_bf16 v[54:57], v[234:237], v[242:245], v[54:57]
	v_mfma_f32_16x16x32_bf16 v[50:53], v[238:241], v[242:245], v[50:53]
	ds_read_b128 v[202:205], v185 offset:15424
	s_waitcnt lgkmcnt(1)
	v_mfma_f32_16x16x32_bf16 v[46:49], v[226:229], v[246:249], v[46:49]
	v_mfma_f32_16x16x32_bf16 v[42:45], v[230:233], v[246:249], v[42:45]
	v_mfma_f32_16x16x32_bf16 v[38:41], v[234:237], v[246:249], v[38:41]
	v_mfma_f32_16x16x32_bf16 v[34:37], v[238:241], v[246:249], v[34:37]
	ds_read_b128 v[206:209], v185 offset:17984
	s_waitcnt lgkmcnt(1)
	v_mfma_f32_16x16x32_bf16 v[30:33], v[226:229], v[202:205], v[30:33]
	v_mfma_f32_16x16x32_bf16 v[26:29], v[230:233], v[202:205], v[26:29]
	v_mfma_f32_16x16x32_bf16 v[22:25], v[234:237], v[202:205], v[22:25]
	v_mfma_f32_16x16x32_bf16 v[18:21], v[238:241], v[202:205], v[18:21]
	s_waitcnt lgkmcnt(0)
	v_mfma_f32_16x16x32_bf16 v[14:17], v[226:229], v[206:209], v[14:17]
	v_mfma_f32_16x16x32_bf16 v[6:9], v[230:233], v[206:209], v[6:9]
	v_mfma_f32_16x16x32_bf16 v[2:5], v[234:237], v[206:209], v[2:5]
	v_mfma_f32_16x16x32_bf16 v[10:13], v[238:241], v[206:209], v[10:13]
	s_setprio 0
	s_barrier
	s_waitcnt vmcnt(7)
	ds_write_b128 v180, v[130:133] offset:10240
	s_waitcnt vmcnt(6)
	ds_write_b128 v180, v[138:141] offset:15360
	s_waitcnt vmcnt(5)
	ds_write_b128 v180, v[146:149] offset:30720
	s_waitcnt vmcnt(4)
	ds_write_b128 v180, v[150:153] offset:35840
	s_waitcnt vmcnt(3)
	ds_write_b128 v180, v[66:69] offset:40960
	s_waitcnt vmcnt(2)
	ds_write_b128 v180, v[70:73] offset:46080
	s_waitcnt vmcnt(1)
	ds_write_b128 v180, v[74:77] offset:51200
	s_waitcnt vmcnt(0)
	ds_write_b128 v180, v[78:81] offset:56320
	s_waitcnt lgkmcnt(0)
	s_barrier
	s_setprio 1
	ds_read_b128 v[202:205], v184 offset:40960
	ds_read_b128 v[206:209], v184 offset:43520
	ds_read_b128 v[214:217], v184 offset:46080
	ds_read_b128 v[218:221], v184 offset:48640
	ds_read_b128 v[210:213], v185 offset:10240
	ds_read_b128 v[222:225], v185 offset:12800
	s_waitcnt lgkmcnt(1)
	v_mfma_f32_16x16x32_bf16 v[62:65], v[202:205], v[210:213], v[62:65]
	v_mfma_f32_16x16x32_bf16 v[58:61], v[206:209], v[210:213], v[58:61]
	v_mfma_f32_16x16x32_bf16 v[54:57], v[214:217], v[210:213], v[54:57]
	v_mfma_f32_16x16x32_bf16 v[50:53], v[218:221], v[210:213], v[50:53]
	ds_read_b128 v[210:213], v185 offset:15360
	s_waitcnt lgkmcnt(1)
	v_mfma_f32_16x16x32_bf16 v[46:49], v[202:205], v[222:225], v[46:49]
	v_mfma_f32_16x16x32_bf16 v[42:45], v[206:209], v[222:225], v[42:45]
	v_mfma_f32_16x16x32_bf16 v[38:41], v[214:217], v[222:225], v[38:41]
	v_mfma_f32_16x16x32_bf16 v[34:37], v[218:221], v[222:225], v[34:37]
	ds_read_b128 v[222:225], v185 offset:17920
	ds_read_b128 v[226:229], v184 offset:41024
	ds_read_b128 v[230:233], v184 offset:43584
	ds_read_b128 v[234:237], v184 offset:46144
	ds_read_b128 v[238:241], v184 offset:48704
	ds_read_b128 v[242:245], v185 offset:10304
	ds_read_b128 v[246:249], v185 offset:12864
	s_waitcnt lgkmcnt(7)
	v_mfma_f32_16x16x32_bf16 v[30:33], v[202:205], v[210:213], v[30:33]
	v_mfma_f32_16x16x32_bf16 v[26:29], v[206:209], v[210:213], v[26:29]
	v_mfma_f32_16x16x32_bf16 v[22:25], v[214:217], v[210:213], v[22:25]
	v_mfma_f32_16x16x32_bf16 v[18:21], v[218:221], v[210:213], v[18:21]
	s_waitcnt lgkmcnt(6)
	v_mfma_f32_16x16x32_bf16 v[14:17], v[202:205], v[222:225], v[14:17]
	v_mfma_f32_16x16x32_bf16 v[6:9], v[206:209], v[222:225], v[6:9]
	v_mfma_f32_16x16x32_bf16 v[2:5], v[214:217], v[222:225], v[2:5]
	v_mfma_f32_16x16x32_bf16 v[10:13], v[218:221], v[222:225], v[10:13]
	s_waitcnt lgkmcnt(1)
	v_mfma_f32_16x16x32_bf16 v[62:65], v[226:229], v[242:245], v[62:65]
	v_mfma_f32_16x16x32_bf16 v[58:61], v[230:233], v[242:245], v[58:61]
	v_mfma_f32_16x16x32_bf16 v[54:57], v[234:237], v[242:245], v[54:57]
	v_mfma_f32_16x16x32_bf16 v[50:53], v[238:241], v[242:245], v[50:53]
	ds_read_b128 v[202:205], v185 offset:15424
	s_waitcnt lgkmcnt(1)
	v_mfma_f32_16x16x32_bf16 v[46:49], v[226:229], v[246:249], v[46:49]
	v_mfma_f32_16x16x32_bf16 v[42:45], v[230:233], v[246:249], v[42:45]
	v_mfma_f32_16x16x32_bf16 v[38:41], v[234:237], v[246:249], v[38:41]
	v_mfma_f32_16x16x32_bf16 v[34:37], v[238:241], v[246:249], v[34:37]
	ds_read_b128 v[206:209], v185 offset:17984
	s_waitcnt lgkmcnt(1)
	v_mfma_f32_16x16x32_bf16 v[30:33], v[226:229], v[202:205], v[30:33]
	v_mfma_f32_16x16x32_bf16 v[26:29], v[230:233], v[202:205], v[26:29]
	v_mfma_f32_16x16x32_bf16 v[22:25], v[234:237], v[202:205], v[22:25]
	v_mfma_f32_16x16x32_bf16 v[18:21], v[238:241], v[202:205], v[18:21]
	s_waitcnt lgkmcnt(0)
	v_mfma_f32_16x16x32_bf16 v[14:17], v[226:229], v[206:209], v[14:17]
	v_mfma_f32_16x16x32_bf16 v[6:9], v[230:233], v[206:209], v[6:9]
	v_mfma_f32_16x16x32_bf16 v[2:5], v[234:237], v[206:209], v[2:5]
	v_mfma_f32_16x16x32_bf16 v[10:13], v[238:241], v[206:209], v[10:13]
	s_setprio 0
	s_branch .LBB0_118
